# seam0 cg grid.sync replaced by the XCD barrier
# speedup vs baseline: 1.0060x; 1.0060x over previous
; #define LAS __attribute__((address_space(3)))
; __device__ __forceinline__ unsigned xb_ld(unsigned* p)              { return __hip_atomic_load(p, __ATOMIC_RELAXED, __HIP_MEMORY_SCOPE_AGENT); }
; __device__ __forceinline__ unsigned xb_xcc_id() { return (unsigned)__builtin_amdgcn_s_getreg((3 << 11) | 20) & 0xFu; }
; __device__ __forceinline__ void xcd_barrier_complete(unsigned* bar, unsigned x, unsigned& nloc, unsigned& nx) {
;     const unsigned G = gridDim.x;
;     unsigned sum, cnt, mine, sp = 0u;
;     for (;;) {
;         sum = 0u; cnt = 0u; mine = 0u;
; #pragma unroll
;         for (unsigned j = 0; j < 16; ++j) { const unsigned c = xb_ld(&bar[XB_XCNT(j)]); sum += c; cnt += (c > 0u) ? 1u : 0u; mine = (j == x) ? c : mine; }
;         if (sum == G) break;
;         __builtin_amdgcn_s_sleep(1);
;         if ((++sp & 255u) == 0u) { if (xb_ld(&bar[XB_TMO])) break; if (sp > XB_SPIN_CAP) { atomicAdd(&bar[XB_TMO], 1u); break; } }
;     }
;     nloc = mine > 0u ? mine : 1u; nx = cnt > 0u ? cnt : 1u;
; }
; __device__ __forceinline__ void xcd_barrier(unsigned* bar, volatile LAS unsigned* st, bool is_t0) {
;     asm volatile("s_waitcnt vmcnt(0)" ::: "memory");
;     __syncthreads();
;     if (is_t0) {
;         __builtin_amdgcn_s_waitcnt(0);
;         const unsigned x = xb_xcc_id();
;         unsigned nloc = st[0], nx = st[1];
;         if (nloc == 0u) { xcd_barrier_complete(bar, x, nloc, nx); st[0] = nloc; st[1] = nx; }
;         const unsigned old = xb_add(&bar[XB_XSUB(x)], 1u);
;         const unsigned gen = old / nloc;
;         if (old + 1u == (gen + 1u) * nloc) {
;             __builtin_amdgcn_fence(__ATOMIC_RELEASE, "agent");
;             asm volatile("s_waitcnt vmcnt(0)" ::: "memory");
;             const unsigned og = xb_add(&bar[XB_TOP], 1u);
;             const unsigned tg = og / nx;
;             if (og + 1u == (tg + 1u) * nx) xb_add(&bar[XB_TOPGEN], 1u);
;             else XB_SPIN(xb_ld(&bar[XB_TOPGEN]) == tg, bar);
;             __builtin_amdgcn_fence(__ATOMIC_ACQUIRE, "agent");
;             xb_add(&bar[XB_XGEN(x)], 1u);
;             asm volatile("s_waitcnt vmcnt(0)" ::: "memory");
;         } else {
;             XB_SPIN(xb_ld(&bar[XB_XGEN(x)]) == gen, bar);
;             __builtin_amdgcn_fence(__ATOMIC_ACQUIRE, "agent");
;             asm volatile("s_waitcnt vmcnt(0)" ::: "memory");
;         }
;     }
;     __syncthreads();
; }
.LBB0_76:
	s_or_b64 exec, exec, s[10:11]
	v_mbcnt_lo_u32_b32 v0, -1, 0
	v_mbcnt_hi_u32_b32 v0, -1, v0
	s_waitcnt vmcnt(0)
	s_waitcnt vmcnt(0)
	v_cmp_eq_u32_e32 vcc, 0, v0
	s_and_b64 s[0:1], vcc, s[36:37]
	s_barrier
	s_and_saveexec_b64 s[4:5], s[0:1]
	s_xor_b64 s[0:1], exec, s[4:5]
	s_cbranch_execz .Lsx0_217
	s_add_i32 s5, 0, 0x24080
	v_mov_b32_e32 v0, s5
	s_waitcnt vmcnt(0) expcnt(0) lgkmcnt(0)
	s_getreg_b32 s4, hwreg(HW_REG_XCC_ID, 0, 4)
	ds_read_b32 v2, v0
	s_add_i32 s5, 0, 0x24084
	v_mov_b32_e32 v0, s5
	ds_read_b32 v0, v0
	s_and_b32 s7, s4, 15
	s_waitcnt lgkmcnt(1)
	v_cmp_ne_u32_e32 vcc, 0, v2
	s_cbranch_vccnz .Lsx0_180
	s_add_u32 s4, s34, 0x1000
	s_addc_u32 s5, s35, 0
	s_add_u32 s8, s34, 0x1100
	s_addc_u32 s9, s35, 0
	s_add_u32 s10, s34, 0x1200
	s_addc_u32 s11, s35, 0
	s_add_u32 s12, s34, 0x1300
	s_addc_u32 s13, s35, 0
	s_mov_b32 s20, 1
	v_mov_b32_e32 v16, 0
	s_branch .Lsx0_168

; #define REP(k) for (int rep_ = 0; rep_ < (((REPMASK >> (k)) & 1) ? 2 : 1); ++rep_)
; #define fresh_tid() ((wave0 << 6) | lane_id_fresh())
; #define SEAM(k) do { if constexpr (COOP) { if (IN(k) && IN((k) + 1)) { if ((k) == CG_SEAM) cg::this_grid().sync(); else xcd_barrier(xbar, xst, lane_id_fresh() == 0 && wave0 == 0); } } } while (0)
;     __device__ bool next(int i, Unit& u) const {
;     ...
;         const long L = (long)ti * G + c; if (L >= nwg) return false;
;         int wgid = (int)L; { const int q = nwg / NXCD, r = nwg % NXCD, xcd = wgid % NXCD, off = wgid / NXCD; wgid = (xcd < r ? xcd * (q + 1) : r * (q + 1) + (xcd - r) * q) + off; }
;         const int nig = wgm * nN, gid = wgid / nig, fm = gid * wgm, gsz = (nM - fm) < wgm ? (nM - fm) : wgm;
;         u.pm = fm + ((wgid % nig) % gsz); u.pn = (wgid % nig) / gsz; return true;
; template <int COOP>
; __global__ void __launch_bounds__(512, 2) mega(Args a) {
;     ...
;     const int lo = a.ph_lo, hi = a.ph_hi;
;     ...
;     if (IN(0)) REP(0) { const Ptrs P = mkptrs(ptab); p0_prologue(P, lds, vcu, G, fresh_tid()); }
;     SEAM(0);
;     if (IN(1)) REP(1) { const Ptrs P = mkptrs(ptab);
;     ...
;         { pg8::Gemm g{P.U, P.W1T, T, 16384, D, D}; pg8::StaticOrder S; S.init(T, 16384, G, bx);
.Lsx0_216:
	s_or_b64 exec, exec, s[8:9]
.Lsx0_217:
	s_or_b64 exec, exec, s[0:1]
	s_cmpk_lt_i32 s2, 0x800
	s_cselect_b64 s[0:1], -1, 0
	s_ashr_i32 s3, s2, 31
	s_lshr_b32 s4, s3, 29
	s_add_i32 s4, s2, s4
	s_ashr_i32 s64, s4, 3
	s_and_b32 s4, s4, -8
	s_sub_i32 s65, s2, s4
	s_cmp_lt_i32 s65, 0
	s_cselect_b64 s[40:41], -1, 0
	s_cmp_gt_i32 s65, -1
	s_cselect_b64 s[38:39], -1, 0
	s_add_i32 s4, 0, 0x24040
	v_mov_b32_e32 v0, s4
	s_add_i32 s4, 0, 0x24060
	s_barrier
	ds_read_b64 v[0:1], v0
	v_mov_b32_e32 v2, s4
	ds_read_b64 v[2:3], v2
	v_mbcnt_lo_u32_b32 v8, -1, 0
	v_mbcnt_hi_u32_b32 v8, -1, v8
	s_and_b64 vcc, exec, s[0:1]
	s_waitcnt lgkmcnt(1)
	v_readfirstlane_b32 s8, v0
	v_or_b32_e32 v0, s33, v8
	v_readfirstlane_b32 s9, v1
	s_waitcnt lgkmcnt(0)
	v_readfirstlane_b32 s7, v3
	v_readfirstlane_b32 s53, v2
	v_readfirstlane_b32 s16, v0
	s_cbranch_vccz .LBB0_88
	s_lshl_b32 s11, s65, 8
	s_mul_i32 s10, s65, 0x101
	s_and_b64 s[4:5], s[40:41], exec
	s_cselect_b32 s4, s10, s11
	s_add_i32 s4, s4, s64
	s_ashr_i32 s5, s4, 31
	s_lshr_b32 s5, s5, 23
	s_add_i32 s5, s4, s5
	s_ashr_i32 s10, s5, 9
	s_and_b32 s5, s5, 0xfe00
	s_sub_i32 s4, s4, s5
	s_sext_i32_i16 s5, s4
	s_bfe_u32 s5, s5, 0x3001c
	s_add_i32 s5, s4, s5
	s_sext_i32_i16 s11, s5
	s_and_b32 s5, s5, 0xfff8
	s_sub_i32 s4, s4, s5
	s_lshl_b32 s10, s10, 3
	s_sext_i32_i16 s4, s4
	s_add_i32 s4, s10, s4
	s_ashr_i32 s18, s11, 3
